# ubuf row blocks stored K-chunk-major (32-KB contiguous chunks): UP epilogue writes 1-KB contiguous per store, down GEMM A loads use the blocked strides
# speedup vs baseline: 1.0238x; 1.0018x over previous
.LBB0_374:
	v_bfe_i32 v2, v12, 27, 1
	v_lshlrev_b32_e32 v0, 4, v12
	v_lshrrev_b32_e32 v2, 22, v2
	v_add_u32_e32 v2, v0, v2
	v_and_b32_e32 v2, 0xfffffc00, v2
	v_ashrrev_i32_e32 v1, 31, v12
	v_sub_u32_e32 v2, v0, v2
	v_lshrrev_b32_e32 v1, 26, v1
	v_lshrrev_b32_e32 v3, 4, v2
	v_add_u32_e32 v1, v12, v1
	v_bitop3_b32 v3, v3, v2, 32 bitop3:0x6c
	v_ashrrev_i32_e32 v2, 31, v2
	v_ashrrev_i32_e32 v1, 6, v1
	v_lshrrev_b32_e32 v2, 26, v2
	v_lshlrev_b32_e32 v4, 3, v1
	v_add_u32_e32 v2, v3, v2
	v_and_b32_e32 v4, -16, v4
	v_ashrrev_i32_e32 v2, 6, v2
	v_lshlrev_b32_e32 v1, 5, v1
	v_add_u32_e32 v4, v2, v4
	v_and_b32_e32 v13, 32, v1
	v_mul_i32_i24_e32 v1, 64, v2
	v_sub_u32_e32 v1, v3, v1
	v_lshlrev_b32_e32 v3, 1, v4
	v_lshrrev_b32_e32 v5, 2, v4
	v_and_b32_e32 v2, 3, v2
	s_mov_b32 s2, 0x7fffffe0
	v_ashrrev_i16_sdwa v1, v227, sext(v1) dst_sel:DWORD dst_unused:UNUSED_PAD src0_sel:DWORD src1_sel:BYTE_0
	v_and_b32_e32 v3, 24, v3
	v_and_b32_e32 v5, 4, v5
	v_and_or_b32 v2, v4, s2, v2
	v_bfe_i32 v14, v1, 0, 16
	v_or3_b32 v2, v2, v5, v3
	v_add_u32_e32 v1, v13, v14
	s_lshl_b32 s99, s82, 8
	s_movk_i32 s100, 0x80
	s_movk_i32 s96, 0x100
	s_mov_b32 s101, 0
	s_cmp_eq_u32 s82, 0x1000
	s_cselect_b32 s98, 64, s82
	s_cselect_b32 s99, 0x4000, s99
	s_cselect_b32 s100, 0x8000, s100
	s_cselect_b32 s96, 0x10000, s96
	v_mul_lo_u32 v15, v4, s98
	v_mul_lo_u32 v2, v2, s82
	v_add_u32_e32 v0, 0x2000, v0
	v_add_lshl_u32 v194, v1, v15, 1
	v_add_lshl_u32 v196, v2, v1, 1
	v_ashrrev_i32_e32 v1, 31, v0
	v_lshrrev_b32_e32 v1, 22, v1
	v_add_u32_e32 v1, v0, v1
	v_ashrrev_i32_e32 v1, 10, v1
	v_mul_i32_i24_e32 v2, 0x400, v1
	v_sub_u32_e32 v0, v0, v2
	v_lshrrev_b32_e32 v2, 4, v0
	v_bitop3_b32 v0, v2, v0, 32 bitop3:0x6c
	v_ashrrev_i32_e32 v3, 31, v0
	v_lshrrev_b32_e32 v3, 26, v3
	v_lshlrev_b32_e32 v2, 3, v1
	v_add_u32_e32 v3, v0, v3
	v_and_b32_e32 v2, -16, v2
	v_ashrrev_i32_e32 v4, 6, v3
	v_lshlrev_b32_e32 v1, 5, v1
	s_ashr_i32 s6, s28, 6
	v_add_u32_e32 v2, v4, v2
	v_and_b32_e32 v16, 32, v1
	v_and_b32_e32 v1, 0xc0, v3
	v_and_b32_e32 v4, 3, v4
	v_sub_u32_e32 v0, v0, v1
	v_lshlrev_b32_e32 v1, 1, v2
	v_lshrrev_b32_e32 v3, 2, v2
	v_and_or_b32 v4, v2, s2, v4
	s_lshl_b32 s2, s6, 10
	v_ashrrev_i16_sdwa v0, v227, sext(v0) dst_sel:DWORD dst_unused:UNUSED_PAD src0_sel:DWORD src1_sel:BYTE_0
	v_and_b32_e32 v1, 24, v1
	v_and_b32_e32 v3, 4, v3
	s_add_i32 s25, s2, 0
	s_ashr_i32 s7, s28, 8
	v_bfe_i32 v17, v0, 0, 16
	v_or3_b32 v1, v4, v3, v1
	s_lshl_b64 s[66:67], s[82:83], 8
	s_add_i32 s74, s25, 0x10000
	s_add_i32 s75, s25, 0x12000
	v_add_u32_e32 v0, v16, v17
	v_mul_lo_u32 v1, v1, s82
	s_mov_b32 m0, s74
	s_add_u32 s8, s62, s66
	v_add_lshl_u32 v200, v1, v0, 1
	global_load_lds_dwordx4 v196, s[62:63]
	s_mov_b32 m0, s75
	s_addc_u32 s9, s63, s67
	s_add_i32 s2, s25, 0x14000
	global_load_lds_dwordx4 v200, s[62:63]
	s_mov_b32 m0, s2
	s_add_i32 s3, s25, 0x16000
	global_load_lds_dwordx4 v196, s[8:9]
	s_mov_b32 m0, s3
	s_add_i32 s31, s25, 0x2000
	v_mul_lo_u32 v18, v2, s98
	s_cmp_eq_u32 s82, 0x1000
	s_cselect_b32 s98, 8, 0
	global_load_lds_dwordx4 v200, s[8:9]
	s_mov_b32 m0, s25
	s_add_u32 s10, s60, s99
	v_add_lshl_u32 v198, v0, v18, 1
	global_load_lds_dwordx4 v194, s[60:61]
	s_mov_b32 m0, s31
	s_addc_u32 s11, s61, 0
	s_add_i32 s15, s25, 0x4000
	global_load_lds_dwordx4 v198, s[60:61]
	s_mov_b32 m0, s15
	s_add_i32 s30, s25, 0x6000
	global_load_lds_dwordx4 v194, s[10:11]
	s_mov_b32 m0, s30
	v_mov_b32_e32 v197, v193
	global_load_lds_dwordx4 v198, s[10:11]
	v_mov_b32_e32 v201, v193
	s_cmp_eq_u32 s7, 1
	v_writelane_b32 v254, s86, 38
	v_lshl_add_u64 v[2:3], s[8:9], 0, v[196:197]
	v_lshl_add_u64 v[0:1], s[8:9], 0, v[200:201]
	s_cselect_b64 s[8:9], -1, 0
	v_writelane_b32 v253, s16, 38
	v_mov_b32_e32 v195, v193
	v_mov_b32_e32 v199, v193
	v_writelane_b32 v254, s8, 40
	v_writelane_b32 v255, s34, 17
	v_writelane_b32 v253, s17, 39
	v_lshl_add_u64 v[8:9], s[62:63], 0, v[196:197]
	v_lshl_add_u64 v[4:5], s[62:63], 0, v[200:201]
	v_lshl_add_u64 v[6:7], s[60:61], 0, v[194:195]
	v_writelane_b32 v254, s9, 41
	s_cmp_lg_u32 s7, 1
	v_lshl_add_u64 v[10:11], s[60:61], 0, v[198:199]
	s_cbranch_scc1 .LBB0_376
	s_barrier
.LBB0_376:
	s_add_i32 s68, s25, 0x18000
	v_lshl_add_u64 v[8:9], v[8:9], 0, s[90:91]
	s_mov_b32 m0, s68
	s_add_i32 s69, s25, 0x1a000
	s_waitcnt vmcnt(2)
	s_barrier
	global_load_lds_dwordx4 v[8:9], off
	v_lshl_add_u64 v[4:5], v[4:5], 0, s[90:91]
	s_mov_b32 m0, s69
	s_add_i32 s73, s25, 0x8000
	global_load_lds_dwordx4 v[4:5], off
	v_lshl_add_u64 v[4:5], v[6:7], 0, s[100:101]
	s_mov_b32 m0, s73
	s_add_i32 s34, s25, 0xa000
	global_load_lds_dwordx4 v[4:5], off
	v_lshl_add_u64 v[4:5], v[10:11], 0, s[100:101]
	s_mov_b32 m0, s34
	s_add_i32 s35, s25, 0x1c000
	global_load_lds_dwordx4 v[4:5], off
	v_lshl_add_u64 v[2:3], v[2:3], 0, s[90:91]
	s_mov_b32 m0, s35
	s_add_i32 s14, s25, 0x1e000
	global_load_lds_dwordx4 v[2:3], off
	v_lshl_add_u64 v[0:1], v[0:1], 0, s[90:91]
	s_mov_b32 m0, s14
	v_bfe_u32 v19, v12, 4, 2
	global_load_lds_dwordx4 v[0:1], off
	s_lshl_b32 s6, s6, 5
	v_and_b32_e32 v239, 15, v12
	v_lshlrev_b32_e32 v20, 4, v19
	v_lshlrev_b32_e32 v12, 2, v12
	s_and_b32 s8, s6, 0x60
	s_lshl_b32 s16, s7, 6
	v_lshl_or_b32 v20, v239, 6, v20
	s_lshl_b32 s7, s7, 13
	v_and_b32_e32 v12, 32, v12
	s_lshl_b32 s6, s8, 7
	s_lshr_b32 s44, s82, 6
	v_bitop3_b32 v21, v20, s7, v12 bitop3:0xde
	v_bitop3_b32 v12, v20, s6, v12 bitop3:0xde
	s_mov_b32 s6, s82
	s_add_i32 s17, s44, -2
	v_writelane_b32 v254, s6, 45
	s_cmpk_lt_u32 s28, 0x100
	s_cselect_b64 s[70:71], -1, 0
	v_writelane_b32 v254, s7, 46
	v_lshl_or_b32 v240, v19, 3, s8
	s_add_u32 s8, s20, 0x1d00000
	v_writelane_b32 v254, s8, 26
	s_addc_u32 s8, s21, 0
	v_writelane_b32 v254, s8, 27
	s_add_u32 s8, s20, 0x1400000
	s_addc_u32 s9, s21, 0
	v_writelane_b32 v254, s8, 43
	v_add_u32_e32 v0, v15, v13
	s_waitcnt vmcnt(6)
	v_add_lshl_u32 v192, v0, v14, 1
	v_writelane_b32 v254, s9, 44
	s_add_u32 s8, s20, 0x1500000
	v_writelane_b32 v254, s8, 34
	s_addc_u32 s8, s21, 0
	s_cmp_lg_u64 s[46:47], 0
	v_writelane_b32 v254, s8, 35
	s_cselect_b64 s[8:9], -1, 0
	v_writelane_b32 v254, s8, 30
	v_add_u32_e32 v0, v18, v16
	v_cmp_eq_u32_e64 s[6:7], 0, v19
	v_writelane_b32 v254, s9, 31
	v_add_u32_e32 v241, 0, v12
	v_readlane_b32 s8, v254, 63
	v_readlane_b32 s9, v255, 0
	s_cmp_lg_u64 s[8:9], 0
	s_cselect_b64 s[8:9], -1, 0
	v_writelane_b32 v254, s8, 14
	v_add_u32_e32 v242, 0, v21
	v_readlane_b32 s45, v253, 40
	v_writelane_b32 v254, s9, 15
	s_add_u32 s8, s99, s100
	s_addc_u32 s9, 0, 0
	v_lshl_add_u64 v[202:203], s[8:9], 0, v[192:193]
	v_add_lshl_u32 v192, v0, v17, 1
	v_mov_b32_e32 v0, 0
	v_lshl_add_u64 v[204:205], s[8:9], 0, v[192:193]
	v_readlane_b32 s52, v253, 0
	v_mov_b32_e32 v1, v0
	v_mov_b32_e32 v2, v0
	v_mov_b32_e32 v3, v0
	v_mov_b32_e32 v4, v0
	v_mov_b32_e32 v5, v0
	v_mov_b32_e32 v6, v0
	v_mov_b32_e32 v7, v0
	v_mov_b32_e32 v8, v0
	v_mov_b32_e32 v9, v0
	v_mov_b32_e32 v10, v0
	v_mov_b32_e32 v11, v0
	v_mov_b32_e32 v12, v0
	v_mov_b32_e32 v13, v0
	v_mov_b32_e32 v14, v0
	v_mov_b32_e32 v15, v0
	v_mov_b32_e32 v16, v0
	v_mov_b32_e32 v17, v0
	v_mov_b32_e32 v18, v0
	v_mov_b32_e32 v19, v0
	v_mov_b32_e32 v20, v0
	v_mov_b32_e32 v21, v0
	v_mov_b32_e32 v22, v0
	v_mov_b32_e32 v23, v0
	v_mov_b32_e32 v24, v0
	v_mov_b32_e32 v25, v0
	v_mov_b32_e32 v26, v0
	v_mov_b32_e32 v27, v0
	v_mov_b32_e32 v28, v0
	v_mov_b32_e32 v29, v0
	v_mov_b32_e32 v30, v0
	v_mov_b32_e32 v31, v0
	v_mov_b32_e32 v32, v0
	v_mov_b32_e32 v33, v0
	v_mov_b32_e32 v34, v0
	v_mov_b32_e32 v35, v0
	v_mov_b32_e32 v36, v0
	v_mov_b32_e32 v37, v0
	v_mov_b32_e32 v38, v0
	v_mov_b32_e32 v39, v0
	v_mov_b32_e32 v40, v0
	v_mov_b32_e32 v41, v0
	v_mov_b32_e32 v42, v0
	v_mov_b32_e32 v43, v0
	v_mov_b32_e32 v44, v0
	v_mov_b32_e32 v45, v0
	v_mov_b32_e32 v46, v0
	v_mov_b32_e32 v47, v0
	v_mov_b32_e32 v48, v0
	v_mov_b32_e32 v49, v0
	v_mov_b32_e32 v50, v0
	v_mov_b32_e32 v51, v0
	v_mov_b32_e32 v56, v0
	v_mov_b32_e32 v57, v0
	v_mov_b32_e32 v58, v0
	v_mov_b32_e32 v59, v0
	v_mov_b32_e32 v64, v0
	v_mov_b32_e32 v65, v0
	v_mov_b32_e32 v66, v0
	v_mov_b32_e32 v67, v0
	v_mov_b32_e32 v72, v0
	v_mov_b32_e32 v73, v0
	v_mov_b32_e32 v74, v0
	v_mov_b32_e32 v75, v0
	v_mov_b32_e32 v80, v0
	v_mov_b32_e32 v81, v0
	v_mov_b32_e32 v82, v0
	v_mov_b32_e32 v83, v0
	v_mov_b32_e32 v88, v0
	v_mov_b32_e32 v89, v0
	v_mov_b32_e32 v90, v0
	v_mov_b32_e32 v91, v0
	v_mov_b32_e32 v96, v0
	v_mov_b32_e32 v97, v0
	v_mov_b32_e32 v98, v0
	v_mov_b32_e32 v99, v0
	v_mov_b32_e32 v104, v0
	v_mov_b32_e32 v105, v0
	v_mov_b32_e32 v106, v0
	v_mov_b32_e32 v107, v0
	v_mov_b32_e32 v52, v0
	v_mov_b32_e32 v53, v0
	v_mov_b32_e32 v54, v0
	v_mov_b32_e32 v55, v0
	v_mov_b32_e32 v60, v0
	v_mov_b32_e32 v61, v0
	v_mov_b32_e32 v62, v0
	v_mov_b32_e32 v63, v0
	v_mov_b32_e32 v68, v0
	v_mov_b32_e32 v69, v0
	v_mov_b32_e32 v70, v0
	v_mov_b32_e32 v71, v0
	v_mov_b32_e32 v76, v0
	v_mov_b32_e32 v77, v0
	v_mov_b32_e32 v78, v0
	v_mov_b32_e32 v79, v0
	v_mov_b32_e32 v84, v0
	v_mov_b32_e32 v85, v0
	v_mov_b32_e32 v86, v0
	v_mov_b32_e32 v87, v0
	v_mov_b32_e32 v92, v0
	v_mov_b32_e32 v93, v0
	v_mov_b32_e32 v94, v0
	v_mov_b32_e32 v95, v0
	v_mov_b32_e32 v100, v0
	v_mov_b32_e32 v101, v0
	v_mov_b32_e32 v102, v0
	v_mov_b32_e32 v103, v0
	v_mov_b32_e32 v108, v0
	v_mov_b32_e32 v109, v0
	v_mov_b32_e32 v110, v0
	v_mov_b32_e32 v111, v0
	v_mov_b32_e32 v112, v0
	v_mov_b32_e32 v113, v0
	v_mov_b32_e32 v114, v0
	v_mov_b32_e32 v115, v0
	v_mov_b32_e32 v116, v0
	v_mov_b32_e32 v117, v0
	v_mov_b32_e32 v118, v0
	v_mov_b32_e32 v119, v0
	v_mov_b32_e32 v120, v0
	v_mov_b32_e32 v121, v0
	v_mov_b32_e32 v122, v0
	v_mov_b32_e32 v123, v0
	v_mov_b32_e32 v124, v0
	v_mov_b32_e32 v125, v0
	v_mov_b32_e32 v126, v0
	v_mov_b32_e32 v127, v0
	s_barrier
	s_branch .LBB0_379

.LBB0_442:
	s_cmp_eq_u32 s17, s53
	v_add_u32_e32 v128, 0x10000, v241
	v_add_u32_e32 v140, 0x14000, v241
	s_cselect_b64 s[12:13], -1, 0
	s_lshl_b64 s[40:41], s[10:11], s98
	s_add_u32 s40, s60, s40
	s_waitcnt lgkmcnt(0)
	ds_read_b128 v[144:147], v128
	ds_read_b128 v[148:151], v128 offset:1024
	ds_read_b128 v[152:155], v128 offset:2048
	ds_read_b128 v[156:159], v128 offset:3072
	ds_read_b128 v[128:131], v140
	ds_read_b128 v[132:135], v140 offset:1024
	ds_read_b128 v[136:139], v140 offset:2048
	ds_read_b128 v[140:143], v140 offset:3072
	s_addc_u32 s41, s61, s41
	s_and_b64 s[8:9], s[12:13], exec
	s_cselect_b32 s43, s85, s41
	s_cselect_b32 s42, s84, s40
	s_add_u32 s50, s62, s10
	s_addc_u32 s51, s63, s11
	s_and_b64 s[8:9], s[78:79], s[12:13]
	s_and_b64 s[12:13], s[12:13], exec
	s_mov_b64 s[40:41], -1
	s_cselect_b32 s13, s87, s51
	s_cselect_b32 s12, s86, s50
	v_lshl_add_u64 v[210:211], s[60:61], 0, v[208:209]
	s_add_i32 m0, s25, 0xc000
	ds_read_b128 v[160:163], v242
	ds_read_b128 v[164:167], v242 offset:1024
	ds_read_b128 v[168:171], v242 offset:2048
	ds_read_b128 v[172:175], v242 offset:3072
	ds_read_b128 v[176:179], v242 offset:4096
	ds_read_b128 v[180:183], v242 offset:5120
	ds_read_b128 v[184:187], v242 offset:6144
	ds_read_b128 v[188:191], v242 offset:7168
	global_load_lds_dwordx4 v[210:211], off
	v_lshl_add_u64 v[210:211], s[60:61], 0, v[206:207]
	s_add_i32 m0, s25, 0xe000
	s_nop 0
	global_load_lds_dwordx4 v[210:211], off
	s_waitcnt vmcnt(8)
	s_waitcnt lgkmcnt(0)
	s_barrier
	s_setprio 1
	s_waitcnt lgkmcnt(0)
	v_mfma_f32_16x16x32_bf16 v[104:107], v[144:147], v[160:163], v[104:107]
	v_mfma_f32_16x16x32_bf16 v[96:99], v[152:155], v[160:163], v[96:99]
	v_mfma_f32_16x16x32_bf16 v[88:91], v[144:147], v[168:171], v[88:91]
	v_mfma_f32_16x16x32_bf16 v[80:83], v[152:155], v[168:171], v[80:83]
	v_mfma_f32_16x16x32_bf16 v[72:75], v[144:147], v[176:179], v[72:75]
	v_mfma_f32_16x16x32_bf16 v[64:67], v[152:155], v[176:179], v[64:67]
	v_mfma_f32_16x16x32_bf16 v[56:59], v[144:147], v[184:187], v[56:59]
	v_mfma_f32_16x16x32_bf16 v[48:51], v[152:155], v[184:187], v[48:51]
	v_mfma_f32_16x16x32_bf16 v[104:107], v[148:151], v[164:167], v[104:107]
	v_mfma_f32_16x16x32_bf16 v[96:99], v[156:159], v[164:167], v[96:99]
	v_mfma_f32_16x16x32_bf16 v[88:91], v[148:151], v[172:175], v[88:91]
	v_mfma_f32_16x16x32_bf16 v[80:83], v[156:159], v[172:175], v[80:83]
	v_mfma_f32_16x16x32_bf16 v[72:75], v[148:151], v[180:183], v[72:75]
	v_mfma_f32_16x16x32_bf16 v[64:67], v[156:159], v[180:183], v[64:67]
	v_mfma_f32_16x16x32_bf16 v[56:59], v[148:151], v[188:191], v[56:59]
	v_mfma_f32_16x16x32_bf16 v[48:51], v[156:159], v[188:191], v[48:51]
	s_setprio 0
	s_setprio 1
	v_mfma_f32_16x16x32_bf16 v[44:47], v[128:131], v[160:163], v[44:47]
	v_mfma_f32_16x16x32_bf16 v[40:43], v[136:139], v[160:163], v[40:43]
	v_mfma_f32_16x16x32_bf16 v[36:39], v[128:131], v[168:171], v[36:39]
	v_mfma_f32_16x16x32_bf16 v[32:35], v[136:139], v[168:171], v[32:35]
	v_mfma_f32_16x16x32_bf16 v[28:31], v[128:131], v[176:179], v[28:31]
	v_mfma_f32_16x16x32_bf16 v[24:27], v[136:139], v[176:179], v[24:27]
	v_mfma_f32_16x16x32_bf16 v[20:23], v[128:131], v[184:187], v[20:23]
	v_mfma_f32_16x16x32_bf16 v[16:19], v[136:139], v[184:187], v[16:19]
	v_mfma_f32_16x16x32_bf16 v[44:47], v[132:135], v[164:167], v[44:47]
	v_mfma_f32_16x16x32_bf16 v[40:43], v[140:143], v[164:167], v[40:43]
	v_mfma_f32_16x16x32_bf16 v[36:39], v[132:135], v[172:175], v[36:39]
	v_mfma_f32_16x16x32_bf16 v[32:35], v[140:143], v[172:175], v[32:35]
	v_mfma_f32_16x16x32_bf16 v[28:31], v[132:135], v[180:183], v[28:31]
	v_mfma_f32_16x16x32_bf16 v[24:27], v[140:143], v[180:183], v[24:27]
	v_mfma_f32_16x16x32_bf16 v[20:23], v[132:135], v[188:191], v[20:23]
	v_mfma_f32_16x16x32_bf16 v[16:19], v[140:143], v[188:191], v[16:19]
	s_setprio 0
	s_barrier
	ds_read_b128 v[184:187], v242 offset:16384
	ds_read_b128 v[188:191], v242 offset:17408
	ds_read_b128 v[176:179], v242 offset:18432
	ds_read_b128 v[180:183], v242 offset:19456
	ds_read_b128 v[168:171], v242 offset:20480
	ds_read_b128 v[172:175], v242 offset:21504
	ds_read_b128 v[160:163], v242 offset:22528
	ds_read_b128 v[164:167], v242 offset:23552
	s_and_b64 vcc, exec, s[8:9]
	v_lshl_add_u64 v[216:217], s[12:13], 0, v[196:197]
	v_lshl_add_u64 v[214:215], s[12:13], 0, v[200:201]
	v_lshl_add_u64 v[212:213], s[42:43], 0, v[194:195]
	v_lshl_add_u64 v[210:211], s[42:43], 0, v[198:199]
	s_cbranch_vccnz .LBB0_444
	s_mov_b32 m0, s74
	s_add_u32 s40, s12, s66
	global_load_lds_dwordx4 v[216:217], off
	s_mov_b32 m0, s75
	s_addc_u32 s41, s13, s67
	global_load_lds_dwordx4 v[214:215], off
	v_lshl_add_u64 v[218:219], s[40:41], 0, v[196:197]
	s_mov_b32 m0, s2
	s_nop 0
	global_load_lds_dwordx4 v[218:219], off
	v_lshl_add_u64 v[218:219], s[40:41], 0, v[200:201]
	s_mov_b32 m0, s3
	s_mov_b64 s[40:41], 0
	global_load_lds_dwordx4 v[218:219], off
	s_mov_b32 m0, s25
	s_nop 0
	global_load_lds_dwordx4 v[212:213], off
	s_mov_b32 m0, s31
	s_nop 0
	global_load_lds_dwordx4 v[210:211], off
	s_waitcnt vmcnt(8)

.LBB0_446:
	s_waitcnt lgkmcnt(0)
	s_xor_b64 vcc, s[8:9], -1
	s_barrier
	s_setprio 1
	s_waitcnt lgkmcnt(0)
	v_mfma_f32_16x16x32_bf16 v[12:15], v[144:147], v[184:187], v[12:15]
	v_mfma_f32_16x16x32_bf16 v[8:11], v[152:155], v[184:187], v[8:11]
	v_mfma_f32_16x16x32_bf16 v[4:7], v[144:147], v[176:179], v[4:7]
	v_mfma_f32_16x16x32_bf16 v[0:3], v[152:155], v[176:179], v[0:3]
	v_mfma_f32_16x16x32_bf16 v[52:55], v[144:147], v[168:171], v[52:55]
	v_mfma_f32_16x16x32_bf16 v[60:63], v[152:155], v[168:171], v[60:63]
	v_mfma_f32_16x16x32_bf16 v[68:71], v[144:147], v[160:163], v[68:71]
	v_mfma_f32_16x16x32_bf16 v[76:79], v[152:155], v[160:163], v[76:79]
	v_mfma_f32_16x16x32_bf16 v[12:15], v[148:151], v[188:191], v[12:15]
	v_mfma_f32_16x16x32_bf16 v[8:11], v[156:159], v[188:191], v[8:11]
	v_mfma_f32_16x16x32_bf16 v[4:7], v[148:151], v[180:183], v[4:7]
	v_mfma_f32_16x16x32_bf16 v[0:3], v[156:159], v[180:183], v[0:3]
	v_mfma_f32_16x16x32_bf16 v[52:55], v[148:151], v[172:175], v[52:55]
	v_mfma_f32_16x16x32_bf16 v[60:63], v[156:159], v[172:175], v[60:63]
	v_mfma_f32_16x16x32_bf16 v[68:71], v[148:151], v[164:167], v[68:71]
	v_mfma_f32_16x16x32_bf16 v[76:79], v[156:159], v[164:167], v[76:79]
	s_setprio 0
	s_setprio 1
	v_mfma_f32_16x16x32_bf16 v[84:87], v[128:131], v[184:187], v[84:87]
	v_mfma_f32_16x16x32_bf16 v[92:95], v[136:139], v[184:187], v[92:95]
	v_mfma_f32_16x16x32_bf16 v[100:103], v[128:131], v[176:179], v[100:103]
	v_mfma_f32_16x16x32_bf16 v[108:111], v[136:139], v[176:179], v[108:111]
	v_mfma_f32_16x16x32_bf16 v[112:115], v[128:131], v[168:171], v[112:115]
	v_mfma_f32_16x16x32_bf16 v[116:119], v[136:139], v[168:171], v[116:119]
	v_mfma_f32_16x16x32_bf16 v[120:123], v[128:131], v[160:163], v[120:123]
	v_mfma_f32_16x16x32_bf16 v[124:127], v[136:139], v[160:163], v[124:127]
	v_mfma_f32_16x16x32_bf16 v[84:87], v[132:135], v[188:191], v[84:87]
	v_mfma_f32_16x16x32_bf16 v[92:95], v[140:143], v[188:191], v[92:95]
	v_mfma_f32_16x16x32_bf16 v[100:103], v[132:135], v[180:183], v[100:103]
	v_mfma_f32_16x16x32_bf16 v[108:111], v[140:143], v[180:183], v[108:111]
	v_mfma_f32_16x16x32_bf16 v[112:115], v[132:135], v[172:175], v[112:115]
	v_mfma_f32_16x16x32_bf16 v[116:119], v[140:143], v[172:175], v[116:119]
	v_mfma_f32_16x16x32_bf16 v[120:123], v[132:135], v[164:167], v[120:123]
	v_mfma_f32_16x16x32_bf16 v[124:127], v[140:143], v[164:167], v[124:127]
	s_setprio 0
	s_barrier
	v_add_u32_e32 v128, 0x18000, v241
	v_add_u32_e32 v140, 0x1c000, v241
	ds_read_b128 v[144:147], v128
	ds_read_b128 v[148:151], v128 offset:1024
	ds_read_b128 v[152:155], v128 offset:2048
	ds_read_b128 v[156:159], v128 offset:3072
	ds_read_b128 v[128:131], v140
	ds_read_b128 v[132:135], v140 offset:1024
	ds_read_b128 v[136:139], v140 offset:2048
	ds_read_b128 v[140:143], v140 offset:3072
	ds_read_b128 v[184:187], v242 offset:32768
	ds_read_b128 v[188:191], v242 offset:33792
	ds_read_b128 v[176:179], v242 offset:34816
	ds_read_b128 v[180:183], v242 offset:35840
	ds_read_b128 v[168:171], v242 offset:36864
	ds_read_b128 v[172:175], v242 offset:37888
	ds_read_b128 v[160:163], v242 offset:38912
	ds_read_b128 v[164:167], v242 offset:39936
	v_cndmask_b32_e64 v192, 0, 1, vcc
	v_cmp_ne_u32_e64 s[8:9], 1, v192
	s_andn2_b64 vcc, exec, vcc
	s_mov_b64 s[40:41], -1
	s_cbranch_vccnz .LBB0_448
	s_add_u32 s40, s42, s99
	s_addc_u32 s41, s43, 0
	s_mov_b32 m0, s15
	v_lshl_add_u64 v[218:219], s[40:41], 0, v[194:195]
	global_load_lds_dwordx4 v[218:219], off
	v_lshl_add_u64 v[218:219], s[40:41], 0, v[198:199]
	s_mov_b32 m0, s30
	s_mov_b64 s[40:41], 0
	global_load_lds_dwordx4 v[218:219], off
	s_waitcnt vmcnt(8)

.LBB0_450:
	s_waitcnt lgkmcnt(0)
	s_barrier
	s_setprio 1
	s_waitcnt lgkmcnt(0)
	v_mfma_f32_16x16x32_bf16 v[104:107], v[144:147], v[184:187], v[104:107]
	v_mfma_f32_16x16x32_bf16 v[96:99], v[152:155], v[184:187], v[96:99]
	v_mfma_f32_16x16x32_bf16 v[88:91], v[144:147], v[176:179], v[88:91]
	v_mfma_f32_16x16x32_bf16 v[80:83], v[152:155], v[176:179], v[80:83]
	v_mfma_f32_16x16x32_bf16 v[72:75], v[144:147], v[168:171], v[72:75]
	v_mfma_f32_16x16x32_bf16 v[64:67], v[152:155], v[168:171], v[64:67]
	v_mfma_f32_16x16x32_bf16 v[56:59], v[144:147], v[160:163], v[56:59]
	v_mfma_f32_16x16x32_bf16 v[48:51], v[152:155], v[160:163], v[48:51]
	v_mfma_f32_16x16x32_bf16 v[104:107], v[148:151], v[188:191], v[104:107]
	v_mfma_f32_16x16x32_bf16 v[96:99], v[156:159], v[188:191], v[96:99]
	v_mfma_f32_16x16x32_bf16 v[88:91], v[148:151], v[180:183], v[88:91]
	v_mfma_f32_16x16x32_bf16 v[80:83], v[156:159], v[180:183], v[80:83]
	v_mfma_f32_16x16x32_bf16 v[72:75], v[148:151], v[172:175], v[72:75]
	v_mfma_f32_16x16x32_bf16 v[64:67], v[156:159], v[172:175], v[64:67]
	v_mfma_f32_16x16x32_bf16 v[56:59], v[148:151], v[164:167], v[56:59]
	v_mfma_f32_16x16x32_bf16 v[48:51], v[156:159], v[164:167], v[48:51]
	s_setprio 0
	s_setprio 1
	v_mfma_f32_16x16x32_bf16 v[44:47], v[128:131], v[184:187], v[44:47]
	v_mfma_f32_16x16x32_bf16 v[40:43], v[136:139], v[184:187], v[40:43]
	v_mfma_f32_16x16x32_bf16 v[36:39], v[128:131], v[176:179], v[36:39]
	v_mfma_f32_16x16x32_bf16 v[32:35], v[136:139], v[176:179], v[32:35]
	v_mfma_f32_16x16x32_bf16 v[28:31], v[128:131], v[168:171], v[28:31]
	v_mfma_f32_16x16x32_bf16 v[24:27], v[136:139], v[168:171], v[24:27]
	v_mfma_f32_16x16x32_bf16 v[20:23], v[128:131], v[160:163], v[20:23]
	v_mfma_f32_16x16x32_bf16 v[16:19], v[136:139], v[160:163], v[16:19]
	v_mfma_f32_16x16x32_bf16 v[44:47], v[132:135], v[188:191], v[44:47]
	v_mfma_f32_16x16x32_bf16 v[40:43], v[140:143], v[188:191], v[40:43]
	v_mfma_f32_16x16x32_bf16 v[36:39], v[132:135], v[180:183], v[36:39]
	v_mfma_f32_16x16x32_bf16 v[32:35], v[140:143], v[180:183], v[32:35]
	v_mfma_f32_16x16x32_bf16 v[28:31], v[132:135], v[172:175], v[28:31]
	v_mfma_f32_16x16x32_bf16 v[24:27], v[140:143], v[172:175], v[24:27]
	v_mfma_f32_16x16x32_bf16 v[20:23], v[132:135], v[164:167], v[20:23]
	v_mfma_f32_16x16x32_bf16 v[16:19], v[140:143], v[164:167], v[16:19]
	s_setprio 0
	s_barrier
	ds_read_b128 v[184:187], v242 offset:49152
	ds_read_b128 v[188:191], v242 offset:50176
	ds_read_b128 v[176:179], v242 offset:51200
	ds_read_b128 v[180:183], v242 offset:52224
	ds_read_b128 v[168:171], v242 offset:53248
	ds_read_b128 v[172:175], v242 offset:54272
	ds_read_b128 v[160:163], v242 offset:55296
	ds_read_b128 v[164:167], v242 offset:56320
	s_and_b64 vcc, exec, s[8:9]
	s_mov_b64 s[8:9], -1
	s_cbranch_vccnz .LBB0_452
	s_mov_b32 m0, s68
	v_lshl_add_u64 v[216:217], v[216:217], 0, s[90:91]
	s_add_u32 s8, s12, s66
	global_load_lds_dwordx4 v[216:217], off
	v_lshl_add_u64 v[214:215], v[214:215], 0, s[90:91]
	s_mov_b32 m0, s69
	s_addc_u32 s9, s13, s67
	global_load_lds_dwordx4 v[214:215], off
	v_lshl_add_u64 v[214:215], s[8:9], 0, v[196:197]
	v_lshl_add_u64 v[214:215], v[214:215], 0, s[90:91]
	s_mov_b32 m0, s35
	v_lshl_add_u64 v[212:213], v[212:213], 0, s[100:101]
	global_load_lds_dwordx4 v[214:215], off
	v_lshl_add_u64 v[214:215], s[8:9], 0, v[200:201]
	v_lshl_add_u64 v[214:215], v[214:215], 0, s[90:91]
	s_mov_b32 m0, s14
	v_lshl_add_u64 v[210:211], v[210:211], 0, s[100:101]
	global_load_lds_dwordx4 v[214:215], off
	s_mov_b32 m0, s73
	s_mov_b64 s[8:9], 0
	global_load_lds_dwordx4 v[212:213], off
	s_mov_b32 m0, s34
	s_nop 0
	global_load_lds_dwordx4 v[210:211], off
	s_waitcnt vmcnt(8)

.LBB0_613:
	s_and_b64 vcc, exec, s[12:13]
	s_cbranch_vccz .LBB0_615
	v_mbcnt_lo_u32_b32 v217, -1, 0
	v_mbcnt_hi_u32_b32 v217, -1, v217
	v_readfirstlane_b32 s100, v240
	v_lshrrev_b32_e32 v216, 3, v240
	v_and_b32_e32 v218, 7, v239
	v_xor_b32_e32 v216, v216, v218
	v_lshlrev_b32_e32 v216, 4, v216
	v_lshl_add_u32 v216, v239, 9, v216
	s_lshl_b32 s101, s16, 7
	s_add_i32 s101, s101, 0xc000
	v_add_u32_e32 v206, s101, v216
	v_add_u32_e32 v207, 0x14400, v206
	v_lshrrev_b32_e32 v218, 3, v217
	v_and_b32_e32 v219, 7, v217
	v_xor_b32_e32 v166, v219, v218
	s_lshr_b32 s101, s100, 5
	s_and_b32 s101, s101, 1
	s_lshl_b32 s101, s101, 4
	v_add_u32_e32 v166, s101, v166
	v_lshlrev_b32_e32 v166, 4, v166
	s_lshr_b32 s101, s100, 6
	s_lshl_b32 s101, s101, 3
	s_lshr_b32 vcc_lo, s16, 2
	s_add_i32 s101, s101, vcc_lo
	v_add_u32_e32 v216, s101, v218
	v_lshl_add_u32 v208, v216, 9, v166
	v_add_u32_e32 v210, 0x20400, v208
	v_add_u32_e32 v208, 0xc000, v208
	s_sub_i32 s101, s43, s16
	s_lshl_b32 s101, s101, 13
	s_lshr_b32 vcc_lo, s100, 6
	s_lshl_b32 vcc_lo, vcc_lo, 3
	s_add_i32 vcc_lo, vcc_lo, s16
	s_lshl_b32 vcc_lo, vcc_lo, 7
	s_add_u32 s101, s101, vcc_lo
	s_lshr_b32 vcc_lo, s42, 6
	s_lshr_b32 vcc_hi, s100, 5
	s_and_b32 vcc_hi, vcc_hi, 1
	s_lshl_b32 vcc_hi, vcc_hi, 1
	s_add_i32 vcc_lo, vcc_lo, vcc_hi
	s_lshl_b32 vcc_lo, vcc_lo, 15
	s_add_u32 s101, s101, vcc_lo
	v_lshlrev_b32_e32 v212, 4, v217
	v_add_u32_e32 v212, s101, v212
	v_mov_b32_e32 v213, 0
	s_nop 0
	v_lshl_add_u64 v[212:213], s[22:23], 0, v[212:213]
	s_mov_b64 s[100:101], 0x8000
	v_lshl_add_u64 v[214:215], v[212:213], 0, s[100:101]
	v_pk_fma_f32 v[172:173], v[104:105], v[160:161], v[140:141] op_sel_hi:[1,0,1]
	v_pk_fma_f32 v[174:175], v[106:107], v[160:161], v[142:143] op_sel_hi:[1,0,1]
	v_pk_fma_f32 v[176:177], v[96:97], v[160:161], v[136:137] op_sel_hi:[1,0,1]
	v_pk_fma_f32 v[178:179], v[98:99], v[160:161], v[138:139] op_sel_hi:[1,0,1]
	v_pk_fma_f32 v[180:181], v[44:45], v[160:161], v[132:133] op_sel_hi:[1,0,1]
	v_pk_fma_f32 v[182:183], v[46:47], v[160:161], v[134:135] op_sel_hi:[1,0,1]
	v_pk_fma_f32 v[184:185], v[40:41], v[160:161], v[128:129] op_sel_hi:[1,0,1]
	v_pk_fma_f32 v[186:187], v[42:43], v[160:161], v[130:131] op_sel_hi:[1,0,1]
	v_max_f32_e32 v172, 0, v172
	v_max_f32_e32 v173, 0, v173
	v_max_f32_e32 v174, 0, v174
	v_max_f32_e32 v175, 0, v175
	v_max_f32_e32 v176, 0, v176
	v_max_f32_e32 v177, 0, v177
	v_max_f32_e32 v178, 0, v178
	v_max_f32_e32 v179, 0, v179
	v_max_f32_e32 v180, 0, v180
	v_max_f32_e32 v181, 0, v181
	v_max_f32_e32 v182, 0, v182
	v_max_f32_e32 v183, 0, v183
	v_max_f32_e32 v184, 0, v184
	v_max_f32_e32 v185, 0, v185
	v_max_f32_e32 v186, 0, v186
	v_max_f32_e32 v187, 0, v187
	v_pk_mul_f32 v[172:173], v[172:173], v[172:173]
	v_pk_mul_f32 v[174:175], v[174:175], v[174:175]
	v_pk_mul_f32 v[176:177], v[176:177], v[176:177]
	v_pk_mul_f32 v[178:179], v[178:179], v[178:179]
	v_pk_mul_f32 v[180:181], v[180:181], v[180:181]
	v_pk_mul_f32 v[182:183], v[182:183], v[182:183]
	v_pk_mul_f32 v[184:185], v[184:185], v[184:185]
	v_pk_mul_f32 v[186:187], v[186:187], v[186:187]
	v_cvt_pk_bf16_f32 v172, v172, v173
	v_cvt_pk_bf16_f32 v180, v180, v181
	v_cvt_pk_bf16_f32 v173, v174, v175
	v_cvt_pk_bf16_f32 v181, v182, v183
	v_cvt_pk_bf16_f32 v174, v176, v177
	v_cvt_pk_bf16_f32 v182, v184, v185
	v_cvt_pk_bf16_f32 v175, v178, v179
	v_cvt_pk_bf16_f32 v183, v186, v187
	ds_write_b128 v206, v[172:175]
	ds_write_b128 v206, v[180:183] offset:256
	s_waitcnt lgkmcnt(0)
	s_barrier
	ds_read_b128 v[162:165], v208
	ds_read_b128 v[188:191], v208 offset:128
	v_pk_fma_f32 v[172:173], v[88:89], v[158:159], v[140:141] op_sel_hi:[1,0,1]
	v_pk_fma_f32 v[174:175], v[90:91], v[158:159], v[142:143] op_sel_hi:[1,0,1]
	v_pk_fma_f32 v[176:177], v[80:81], v[158:159], v[136:137] op_sel_hi:[1,0,1]
	v_pk_fma_f32 v[178:179], v[82:83], v[158:159], v[138:139] op_sel_hi:[1,0,1]
	v_pk_fma_f32 v[180:181], v[36:37], v[158:159], v[132:133] op_sel_hi:[1,0,1]
	v_pk_fma_f32 v[182:183], v[38:39], v[158:159], v[134:135] op_sel_hi:[1,0,1]
	v_pk_fma_f32 v[184:185], v[32:33], v[158:159], v[128:129] op_sel_hi:[1,0,1]
	v_pk_fma_f32 v[186:187], v[34:35], v[158:159], v[130:131] op_sel_hi:[1,0,1]
	v_max_f32_e32 v172, 0, v172
	v_max_f32_e32 v173, 0, v173
	v_max_f32_e32 v174, 0, v174
	v_max_f32_e32 v175, 0, v175
	v_max_f32_e32 v176, 0, v176
	v_max_f32_e32 v177, 0, v177
	v_max_f32_e32 v178, 0, v178
	v_max_f32_e32 v179, 0, v179
	v_max_f32_e32 v180, 0, v180
	v_max_f32_e32 v181, 0, v181
	v_max_f32_e32 v182, 0, v182
	v_max_f32_e32 v183, 0, v183
	v_max_f32_e32 v184, 0, v184
	v_max_f32_e32 v185, 0, v185
	v_max_f32_e32 v186, 0, v186
	v_max_f32_e32 v187, 0, v187
	v_pk_mul_f32 v[172:173], v[172:173], v[172:173]
	v_pk_mul_f32 v[174:175], v[174:175], v[174:175]
	v_pk_mul_f32 v[176:177], v[176:177], v[176:177]
	v_pk_mul_f32 v[178:179], v[178:179], v[178:179]
	v_pk_mul_f32 v[180:181], v[180:181], v[180:181]
	v_pk_mul_f32 v[182:183], v[182:183], v[182:183]
	v_pk_mul_f32 v[184:185], v[184:185], v[184:185]
	v_pk_mul_f32 v[186:187], v[186:187], v[186:187]
	v_cvt_pk_bf16_f32 v172, v172, v173
	v_cvt_pk_bf16_f32 v180, v180, v181
	v_cvt_pk_bf16_f32 v173, v174, v175
	v_cvt_pk_bf16_f32 v181, v182, v183
	v_cvt_pk_bf16_f32 v174, v176, v177
	v_cvt_pk_bf16_f32 v182, v184, v185
	v_cvt_pk_bf16_f32 v175, v178, v179
	v_cvt_pk_bf16_f32 v183, v186, v187
	s_waitcnt lgkmcnt(0)
	global_store_dwordx4 v[212:213], v[162:165], off
	global_store_dwordx4 v[214:215], v[188:191], off
	s_mov_b64 s[100:101], 0x800
	ds_write_b128 v207, v[172:175]
	ds_write_b128 v207, v[180:183] offset:256
	v_lshl_add_u64 v[212:213], v[212:213], 0, s[100:101]
	v_lshl_add_u64 v[214:215], v[214:215], 0, s[100:101]
	s_waitcnt lgkmcnt(0)
	s_barrier
	ds_read_b128 v[162:165], v210
	ds_read_b128 v[188:191], v210 offset:128
	v_pk_fma_f32 v[172:173], v[72:73], v[156:157], v[140:141] op_sel_hi:[1,0,1]
	v_pk_fma_f32 v[174:175], v[74:75], v[156:157], v[142:143] op_sel_hi:[1,0,1]
	v_pk_fma_f32 v[176:177], v[64:65], v[156:157], v[136:137] op_sel_hi:[1,0,1]
	v_pk_fma_f32 v[178:179], v[66:67], v[156:157], v[138:139] op_sel_hi:[1,0,1]
	v_pk_fma_f32 v[180:181], v[28:29], v[156:157], v[132:133] op_sel_hi:[1,0,1]
	v_pk_fma_f32 v[182:183], v[30:31], v[156:157], v[134:135] op_sel_hi:[1,0,1]
	v_pk_fma_f32 v[184:185], v[24:25], v[156:157], v[128:129] op_sel_hi:[1,0,1]
	v_pk_fma_f32 v[186:187], v[26:27], v[156:157], v[130:131] op_sel_hi:[1,0,1]
	v_max_f32_e32 v172, 0, v172
	v_max_f32_e32 v173, 0, v173
	v_max_f32_e32 v174, 0, v174
	v_max_f32_e32 v175, 0, v175
	v_max_f32_e32 v176, 0, v176
	v_max_f32_e32 v177, 0, v177
	v_max_f32_e32 v178, 0, v178
	v_max_f32_e32 v179, 0, v179
	v_max_f32_e32 v180, 0, v180
	v_max_f32_e32 v181, 0, v181
	v_max_f32_e32 v182, 0, v182
	v_max_f32_e32 v183, 0, v183
	v_max_f32_e32 v184, 0, v184
	v_max_f32_e32 v185, 0, v185
	v_max_f32_e32 v186, 0, v186
	v_max_f32_e32 v187, 0, v187
	v_pk_mul_f32 v[172:173], v[172:173], v[172:173]
	v_pk_mul_f32 v[174:175], v[174:175], v[174:175]
	v_pk_mul_f32 v[176:177], v[176:177], v[176:177]
	v_pk_mul_f32 v[178:179], v[178:179], v[178:179]
	v_pk_mul_f32 v[180:181], v[180:181], v[180:181]
	v_pk_mul_f32 v[182:183], v[182:183], v[182:183]
	v_pk_mul_f32 v[184:185], v[184:185], v[184:185]
	v_pk_mul_f32 v[186:187], v[186:187], v[186:187]
	v_cvt_pk_bf16_f32 v172, v172, v173
	v_cvt_pk_bf16_f32 v180, v180, v181
	v_cvt_pk_bf16_f32 v173, v174, v175
	v_cvt_pk_bf16_f32 v181, v182, v183
	v_cvt_pk_bf16_f32 v174, v176, v177
	v_cvt_pk_bf16_f32 v182, v184, v185
	v_cvt_pk_bf16_f32 v175, v178, v179
	v_cvt_pk_bf16_f32 v183, v186, v187
	s_waitcnt lgkmcnt(0)
	global_store_dwordx4 v[212:213], v[162:165], off
	global_store_dwordx4 v[214:215], v[188:191], off
	s_mov_b64 s[100:101], 0x800
	ds_write_b128 v206, v[172:175]
	ds_write_b128 v206, v[180:183] offset:256
	v_lshl_add_u64 v[212:213], v[212:213], 0, s[100:101]
	v_lshl_add_u64 v[214:215], v[214:215], 0, s[100:101]
	s_waitcnt lgkmcnt(0)
	s_barrier
	ds_read_b128 v[162:165], v208
	ds_read_b128 v[188:191], v208 offset:128
	v_pk_fma_f32 v[172:173], v[56:57], v[154:155], v[140:141] op_sel_hi:[1,0,1]
	v_pk_fma_f32 v[174:175], v[58:59], v[154:155], v[142:143] op_sel_hi:[1,0,1]
	v_pk_fma_f32 v[176:177], v[48:49], v[154:155], v[136:137] op_sel_hi:[1,0,1]
	v_pk_fma_f32 v[178:179], v[50:51], v[154:155], v[138:139] op_sel_hi:[1,0,1]
	v_pk_fma_f32 v[180:181], v[20:21], v[154:155], v[132:133] op_sel_hi:[1,0,1]
	v_pk_fma_f32 v[182:183], v[22:23], v[154:155], v[134:135] op_sel_hi:[1,0,1]
	v_pk_fma_f32 v[184:185], v[16:17], v[154:155], v[128:129] op_sel_hi:[1,0,1]
	v_pk_fma_f32 v[186:187], v[18:19], v[154:155], v[130:131] op_sel_hi:[1,0,1]
	v_max_f32_e32 v172, 0, v172
	v_max_f32_e32 v173, 0, v173
	v_max_f32_e32 v174, 0, v174
	v_max_f32_e32 v175, 0, v175
	v_max_f32_e32 v176, 0, v176
	v_max_f32_e32 v177, 0, v177
	v_max_f32_e32 v178, 0, v178
	v_max_f32_e32 v179, 0, v179
	v_max_f32_e32 v180, 0, v180
	v_max_f32_e32 v181, 0, v181
	v_max_f32_e32 v182, 0, v182
	v_max_f32_e32 v183, 0, v183
	v_max_f32_e32 v184, 0, v184
	v_max_f32_e32 v185, 0, v185
	v_max_f32_e32 v186, 0, v186
	v_max_f32_e32 v187, 0, v187
	v_pk_mul_f32 v[172:173], v[172:173], v[172:173]
	v_pk_mul_f32 v[174:175], v[174:175], v[174:175]
	v_pk_mul_f32 v[176:177], v[176:177], v[176:177]
	v_pk_mul_f32 v[178:179], v[178:179], v[178:179]
	v_pk_mul_f32 v[180:181], v[180:181], v[180:181]
	v_pk_mul_f32 v[182:183], v[182:183], v[182:183]
	v_pk_mul_f32 v[184:185], v[184:185], v[184:185]
	v_pk_mul_f32 v[186:187], v[186:187], v[186:187]
	v_cvt_pk_bf16_f32 v172, v172, v173
	v_cvt_pk_bf16_f32 v180, v180, v181
	v_cvt_pk_bf16_f32 v173, v174, v175
	v_cvt_pk_bf16_f32 v181, v182, v183
	v_cvt_pk_bf16_f32 v174, v176, v177
	v_cvt_pk_bf16_f32 v182, v184, v185
	v_cvt_pk_bf16_f32 v175, v178, v179
	v_cvt_pk_bf16_f32 v183, v186, v187
	s_waitcnt lgkmcnt(0)
	global_store_dwordx4 v[212:213], v[162:165], off
	global_store_dwordx4 v[214:215], v[188:191], off
	s_mov_b64 s[100:101], 0x800
	ds_write_b128 v207, v[172:175]
	ds_write_b128 v207, v[180:183] offset:256
	v_lshl_add_u64 v[212:213], v[212:213], 0, s[100:101]
	v_lshl_add_u64 v[214:215], v[214:215], 0, s[100:101]
	s_waitcnt lgkmcnt(0)
	s_barrier
	ds_read_b128 v[162:165], v210
	ds_read_b128 v[188:191], v210 offset:128
	v_pk_fma_f32 v[172:173], v[12:13], v[150:151], v[140:141] op_sel_hi:[1,0,1]
	v_pk_fma_f32 v[174:175], v[14:15], v[150:151], v[142:143] op_sel_hi:[1,0,1]
	v_pk_fma_f32 v[176:177], v[8:9], v[150:151], v[136:137] op_sel_hi:[1,0,1]
	v_pk_fma_f32 v[178:179], v[10:11], v[150:151], v[138:139] op_sel_hi:[1,0,1]
	v_pk_fma_f32 v[180:181], v[84:85], v[150:151], v[132:133] op_sel_hi:[1,0,1]
	v_pk_fma_f32 v[182:183], v[86:87], v[150:151], v[134:135] op_sel_hi:[1,0,1]
	v_pk_fma_f32 v[184:185], v[92:93], v[150:151], v[128:129] op_sel_hi:[1,0,1]
	v_pk_fma_f32 v[186:187], v[94:95], v[150:151], v[130:131] op_sel_hi:[1,0,1]
	v_max_f32_e32 v172, 0, v172
	v_max_f32_e32 v173, 0, v173
	v_max_f32_e32 v174, 0, v174
	v_max_f32_e32 v175, 0, v175
	v_max_f32_e32 v176, 0, v176
	v_max_f32_e32 v177, 0, v177
	v_max_f32_e32 v178, 0, v178
	v_max_f32_e32 v179, 0, v179
	v_max_f32_e32 v180, 0, v180
	v_max_f32_e32 v181, 0, v181
	v_max_f32_e32 v182, 0, v182
	v_max_f32_e32 v183, 0, v183
	v_max_f32_e32 v184, 0, v184
	v_max_f32_e32 v185, 0, v185
	v_max_f32_e32 v186, 0, v186
	v_max_f32_e32 v187, 0, v187
	v_pk_mul_f32 v[172:173], v[172:173], v[172:173]
	v_pk_mul_f32 v[174:175], v[174:175], v[174:175]
	v_pk_mul_f32 v[176:177], v[176:177], v[176:177]
	v_pk_mul_f32 v[178:179], v[178:179], v[178:179]
	v_pk_mul_f32 v[180:181], v[180:181], v[180:181]
	v_pk_mul_f32 v[182:183], v[182:183], v[182:183]
	v_pk_mul_f32 v[184:185], v[184:185], v[184:185]
	v_pk_mul_f32 v[186:187], v[186:187], v[186:187]
	v_cvt_pk_bf16_f32 v172, v172, v173
	v_cvt_pk_bf16_f32 v180, v180, v181
	v_cvt_pk_bf16_f32 v173, v174, v175
	v_cvt_pk_bf16_f32 v181, v182, v183
	v_cvt_pk_bf16_f32 v174, v176, v177
	v_cvt_pk_bf16_f32 v182, v184, v185
	v_cvt_pk_bf16_f32 v175, v178, v179
	v_cvt_pk_bf16_f32 v183, v186, v187
	s_waitcnt lgkmcnt(0)
	global_store_dwordx4 v[212:213], v[162:165], off
	global_store_dwordx4 v[214:215], v[188:191], off
	s_mov_b64 s[100:101], 0x2800
	ds_write_b128 v206, v[172:175]
	ds_write_b128 v206, v[180:183] offset:256
	v_lshl_add_u64 v[212:213], v[212:213], 0, s[100:101]
	v_lshl_add_u64 v[214:215], v[214:215], 0, s[100:101]
	s_waitcnt lgkmcnt(0)
	s_barrier
	ds_read_b128 v[162:165], v208
	ds_read_b128 v[188:191], v208 offset:128
	v_pk_fma_f32 v[172:173], v[4:5], v[148:149], v[140:141] op_sel_hi:[1,0,1]
	v_pk_fma_f32 v[174:175], v[6:7], v[148:149], v[142:143] op_sel_hi:[1,0,1]
	v_pk_fma_f32 v[176:177], v[0:1], v[148:149], v[136:137] op_sel_hi:[1,0,1]
	v_pk_fma_f32 v[178:179], v[2:3], v[148:149], v[138:139] op_sel_hi:[1,0,1]
	v_pk_fma_f32 v[180:181], v[100:101], v[148:149], v[132:133] op_sel_hi:[1,0,1]
	v_pk_fma_f32 v[182:183], v[102:103], v[148:149], v[134:135] op_sel_hi:[1,0,1]
	v_pk_fma_f32 v[184:185], v[108:109], v[148:149], v[128:129] op_sel_hi:[1,0,1]
	v_pk_fma_f32 v[186:187], v[110:111], v[148:149], v[130:131] op_sel_hi:[1,0,1]
	v_max_f32_e32 v172, 0, v172
	v_max_f32_e32 v173, 0, v173
	v_max_f32_e32 v174, 0, v174
	v_max_f32_e32 v175, 0, v175
	v_max_f32_e32 v176, 0, v176
	v_max_f32_e32 v177, 0, v177
	v_max_f32_e32 v178, 0, v178
	v_max_f32_e32 v179, 0, v179
	v_max_f32_e32 v180, 0, v180
	v_max_f32_e32 v181, 0, v181
	v_max_f32_e32 v182, 0, v182
	v_max_f32_e32 v183, 0, v183
	v_max_f32_e32 v184, 0, v184
	v_max_f32_e32 v185, 0, v185
	v_max_f32_e32 v186, 0, v186
	v_max_f32_e32 v187, 0, v187
	v_pk_mul_f32 v[172:173], v[172:173], v[172:173]
	v_pk_mul_f32 v[174:175], v[174:175], v[174:175]
	v_pk_mul_f32 v[176:177], v[176:177], v[176:177]
	v_pk_mul_f32 v[178:179], v[178:179], v[178:179]
	v_pk_mul_f32 v[180:181], v[180:181], v[180:181]
	v_pk_mul_f32 v[182:183], v[182:183], v[182:183]
	v_pk_mul_f32 v[184:185], v[184:185], v[184:185]
	v_pk_mul_f32 v[186:187], v[186:187], v[186:187]
	v_cvt_pk_bf16_f32 v172, v172, v173
	v_cvt_pk_bf16_f32 v180, v180, v181
	v_cvt_pk_bf16_f32 v173, v174, v175
	v_cvt_pk_bf16_f32 v181, v182, v183
	v_cvt_pk_bf16_f32 v174, v176, v177
	v_cvt_pk_bf16_f32 v182, v184, v185
	v_cvt_pk_bf16_f32 v175, v178, v179
	v_cvt_pk_bf16_f32 v183, v186, v187
	s_waitcnt lgkmcnt(0)
	global_store_dwordx4 v[212:213], v[162:165], off
	global_store_dwordx4 v[214:215], v[188:191], off
	s_mov_b64 s[100:101], 0x800
	ds_write_b128 v207, v[172:175]
	ds_write_b128 v207, v[180:183] offset:256
	v_lshl_add_u64 v[212:213], v[212:213], 0, s[100:101]
	v_lshl_add_u64 v[214:215], v[214:215], 0, s[100:101]
	s_waitcnt lgkmcnt(0)
	s_barrier
	ds_read_b128 v[162:165], v210
	ds_read_b128 v[188:191], v210 offset:128
	v_pk_fma_f32 v[172:173], v[52:53], v[146:147], v[140:141] op_sel_hi:[1,0,1]
	v_pk_fma_f32 v[174:175], v[54:55], v[146:147], v[142:143] op_sel_hi:[1,0,1]
	v_pk_fma_f32 v[176:177], v[60:61], v[146:147], v[136:137] op_sel_hi:[1,0,1]
	v_pk_fma_f32 v[178:179], v[62:63], v[146:147], v[138:139] op_sel_hi:[1,0,1]
	v_pk_fma_f32 v[180:181], v[112:113], v[146:147], v[132:133] op_sel_hi:[1,0,1]
	v_pk_fma_f32 v[182:183], v[114:115], v[146:147], v[134:135] op_sel_hi:[1,0,1]
	v_pk_fma_f32 v[184:185], v[116:117], v[146:147], v[128:129] op_sel_hi:[1,0,1]
	v_pk_fma_f32 v[186:187], v[118:119], v[146:147], v[130:131] op_sel_hi:[1,0,1]
	v_max_f32_e32 v172, 0, v172
	v_max_f32_e32 v173, 0, v173
	v_max_f32_e32 v174, 0, v174
	v_max_f32_e32 v175, 0, v175
	v_max_f32_e32 v176, 0, v176
	v_max_f32_e32 v177, 0, v177
	v_max_f32_e32 v178, 0, v178
	v_max_f32_e32 v179, 0, v179
	v_max_f32_e32 v180, 0, v180
	v_max_f32_e32 v181, 0, v181
	v_max_f32_e32 v182, 0, v182
	v_max_f32_e32 v183, 0, v183
	v_max_f32_e32 v184, 0, v184
	v_max_f32_e32 v185, 0, v185
	v_max_f32_e32 v186, 0, v186
	v_max_f32_e32 v187, 0, v187
	v_pk_mul_f32 v[172:173], v[172:173], v[172:173]
	v_pk_mul_f32 v[174:175], v[174:175], v[174:175]
	v_pk_mul_f32 v[176:177], v[176:177], v[176:177]
	v_pk_mul_f32 v[178:179], v[178:179], v[178:179]
	v_pk_mul_f32 v[180:181], v[180:181], v[180:181]
	v_pk_mul_f32 v[182:183], v[182:183], v[182:183]
	v_pk_mul_f32 v[184:185], v[184:185], v[184:185]
	v_pk_mul_f32 v[186:187], v[186:187], v[186:187]
	v_cvt_pk_bf16_f32 v172, v172, v173
	v_cvt_pk_bf16_f32 v180, v180, v181
	v_cvt_pk_bf16_f32 v173, v174, v175
	v_cvt_pk_bf16_f32 v181, v182, v183
	v_cvt_pk_bf16_f32 v174, v176, v177
	v_cvt_pk_bf16_f32 v182, v184, v185
	v_cvt_pk_bf16_f32 v175, v178, v179
	v_cvt_pk_bf16_f32 v183, v186, v187
	s_waitcnt lgkmcnt(0)
	global_store_dwordx4 v[212:213], v[162:165], off
	global_store_dwordx4 v[214:215], v[188:191], off
	s_mov_b64 s[100:101], 0x800
	ds_write_b128 v206, v[172:175]
	ds_write_b128 v206, v[180:183] offset:256
	v_lshl_add_u64 v[212:213], v[212:213], 0, s[100:101]
	v_lshl_add_u64 v[214:215], v[214:215], 0, s[100:101]
	s_waitcnt lgkmcnt(0)
	s_barrier
	ds_read_b128 v[162:165], v208
	ds_read_b128 v[188:191], v208 offset:128
	v_pk_fma_f32 v[172:173], v[68:69], v[144:145], v[140:141] op_sel_hi:[1,0,1]
	v_pk_fma_f32 v[174:175], v[70:71], v[144:145], v[142:143] op_sel_hi:[1,0,1]
	v_pk_fma_f32 v[176:177], v[76:77], v[144:145], v[136:137] op_sel_hi:[1,0,1]
	v_pk_fma_f32 v[178:179], v[78:79], v[144:145], v[138:139] op_sel_hi:[1,0,1]
	v_pk_fma_f32 v[180:181], v[120:121], v[144:145], v[132:133] op_sel_hi:[1,0,1]
	v_pk_fma_f32 v[182:183], v[122:123], v[144:145], v[134:135] op_sel_hi:[1,0,1]
	v_pk_fma_f32 v[184:185], v[124:125], v[144:145], v[128:129] op_sel_hi:[1,0,1]
	v_pk_fma_f32 v[186:187], v[126:127], v[144:145], v[130:131] op_sel_hi:[1,0,1]
	v_max_f32_e32 v172, 0, v172
	v_max_f32_e32 v173, 0, v173
	v_max_f32_e32 v174, 0, v174
	v_max_f32_e32 v175, 0, v175
	v_max_f32_e32 v176, 0, v176
	v_max_f32_e32 v177, 0, v177
	v_max_f32_e32 v178, 0, v178
	v_max_f32_e32 v179, 0, v179
	v_max_f32_e32 v180, 0, v180
	v_max_f32_e32 v181, 0, v181
	v_max_f32_e32 v182, 0, v182
	v_max_f32_e32 v183, 0, v183
	v_max_f32_e32 v184, 0, v184
	v_max_f32_e32 v185, 0, v185
	v_max_f32_e32 v186, 0, v186
	v_max_f32_e32 v187, 0, v187
	v_pk_mul_f32 v[172:173], v[172:173], v[172:173]
	v_pk_mul_f32 v[174:175], v[174:175], v[174:175]
	v_pk_mul_f32 v[176:177], v[176:177], v[176:177]
	v_pk_mul_f32 v[178:179], v[178:179], v[178:179]
	v_pk_mul_f32 v[180:181], v[180:181], v[180:181]
	v_pk_mul_f32 v[182:183], v[182:183], v[182:183]
	v_pk_mul_f32 v[184:185], v[184:185], v[184:185]
	v_pk_mul_f32 v[186:187], v[186:187], v[186:187]
	v_cvt_pk_bf16_f32 v172, v172, v173
	v_cvt_pk_bf16_f32 v180, v180, v181
	v_cvt_pk_bf16_f32 v173, v174, v175
	v_cvt_pk_bf16_f32 v181, v182, v183
	v_cvt_pk_bf16_f32 v174, v176, v177
	v_cvt_pk_bf16_f32 v182, v184, v185
	v_cvt_pk_bf16_f32 v175, v178, v179
	v_cvt_pk_bf16_f32 v183, v186, v187
	s_waitcnt lgkmcnt(0)
	global_store_dwordx4 v[212:213], v[162:165], off
	global_store_dwordx4 v[214:215], v[188:191], off
	s_mov_b64 s[100:101], 0x800
	ds_write_b128 v207, v[172:175]
	ds_write_b128 v207, v[180:183] offset:256
	v_lshl_add_u64 v[212:213], v[212:213], 0, s[100:101]
	v_lshl_add_u64 v[214:215], v[214:215], 0, s[100:101]
	s_waitcnt lgkmcnt(0)
	s_barrier
	ds_read_b128 v[162:165], v210
	ds_read_b128 v[188:191], v210 offset:128
	s_waitcnt lgkmcnt(0)
	global_store_dwordx4 v[212:213], v[162:165], off
	global_store_dwordx4 v[214:215], v[188:191], off
	s_movk_i32 s100, 0x80
	s_mov_b32 s101, 0
